# baseline (speedup 1.0000x reference)
;     ...
;     for (int ai = 0; ai < 2; ++ai)
; #pragma unroll
;       for (int m = 0; m < 4; ++m) {
;         const int row = brow + ai * HALF + wr * 64 + m * 16 + fr;
;         float ssq = 0.f;
; #pragma unroll
;         for (int bj = 0; bj < 2; ++bj)
; #pragma unroll
;           for (int n = 0; n < 2; ++n) {
;             const int col = bcol + bj * HALF + wc * 32 + n * 16 + fq * 4;
;             f32x4 v = acc[ai][bj][m][n];
;             v += *(const f32x4*)(res + (long)row * D + col);
;             if (EPI == 7) *(f32x4*)(outf + (long)row * D + col) = v;
;             acc[ai][bj][m][n] = v;
;             ssq += v[0] * v[0] + v[1] * v[1] + v[2] * v[2] + v[3] * v[3];
;           }
;         ssq += bperm(ssq, lane ^ 16);
;         ssq += bperm(ssq, lane ^ 32);
;         if (fq == 0) p->sspart[(long)row * 64 + pn_ * 4 + wc] = ssq;
.LBB0_1145:
	s_or_b64 exec, exec, s[28:29]
	s_nop 0
	v_or_b32_e32 v12, s24, v142
	v_lshrrev_b32_e32 v13, 2, v140
	v_add_u32_e32 v142, v143, v12
	v_lshlrev_b32_e32 v12, 5, v141
	v_and_b32_e32 v13, 12, v13
	v_or3_b32 v138, v12, v13, s26
	v_ashrrev_i32_e32 v143, 31, v142
	v_lshlrev_b64 v[146:147], 14, v[142:143]
	v_ashrrev_i32_e32 v139, 31, v138
	v_lshl_add_u64 v[12:13], s[10:11], 0, v[146:147]
	v_lshlrev_b64 v[144:145], 2, v[138:139]
	v_lshl_add_u64 v[24:25], v[12:13], 0, v[144:145]
	global_load_dwordx4 v[12:15], v[24:25], off nt
	global_load_dwordx4 v[100:103], v[24:25], off offset:64 nt
	global_load_dwordx4 v[154:157], v[24:25], off offset:512 nt
	global_load_dwordx4 v[158:161], v[24:25], off offset:576 nt
	v_and_b32_e32 v24, 63, v140
	v_lshlrev_b32_e32 v25, 2, v24
	v_cmp_gt_u32_e32 vcc, 16, v24
	v_xor_b32_e32 v153, 64, v25
	v_xor_b32_e32 v152, 0x80, v25
	s_ashr_i32 s25, s45, 1
	s_and_b32 s26, s25, -4
	s_ashr_i32 s27, s26, 31
	v_lshlrev_b32_e32 v136, 2, v141
	s_waitcnt vmcnt(0)
	v_pk_add_f32 v[24:25], v[0:1], v[12:13]
	v_pk_add_f32 v[12:13], v[4:5], v[100:101]
	v_pk_add_f32 v[4:5], v[40:41], v[154:155]
	v_pk_add_f32 v[0:1], v[32:33], v[158:159]
	v_mul_f32_e32 v32, v25, v25
	v_mul_f32_e32 v33, v13, v13
	v_pk_add_f32 v[26:27], v[2:3], v[14:15]
	v_pk_add_f32 v[14:15], v[6:7], v[102:103]
	v_pk_add_f32 v[2:3], v[34:35], v[160:161]
	v_mul_f32_e32 v34, v5, v5
	v_fmac_f32_e32 v32, v24, v24
	v_fmac_f32_e32 v33, v12, v12
	v_pk_add_f32 v[6:7], v[42:43], v[156:157]
	v_mul_f32_e32 v35, v1, v1
	v_fmac_f32_e32 v34, v4, v4
	v_fmac_f32_e32 v32, v26, v26
	v_fmac_f32_e32 v33, v14, v14
	v_fmac_f32_e32 v35, v0, v0
	v_fmac_f32_e32 v34, v6, v6
	v_fmac_f32_e32 v32, v27, v27
	v_fmac_f32_e32 v33, v15, v15
	v_fmac_f32_e32 v35, v2, v2
	v_fmac_f32_e32 v34, v7, v7
	v_add_f32_e32 v32, v32, v33
	v_add_f32_e32 v32, v32, v34
	v_fmac_f32_e32 v35, v3, v3
	v_add_f32_e32 v40, v32, v35
	ds_bpermute_b32 v41, v153, v40
	v_lshl_add_u64 v[32:33], s[6:7], 0, v[146:147]
	v_lshl_add_u64 v[34:35], v[32:33], 0, v[144:145]
	global_store_dwordx4 v[34:35], v[24:27], off
	global_store_dwordx4 v[34:35], v[12:15], off offset:64
	global_store_dwordx4 v[34:35], v[4:7], off offset:512
	global_store_dwordx4 v[34:35], v[0:3], off offset:576
	s_waitcnt lgkmcnt(0)
	v_add_f32_e32 v32, v40, v41
	ds_bpermute_b32 v33, v152, v32
	s_and_saveexec_b64 s[28:29], vcc
	s_cbranch_execz .LBB0_1147
	s_load_dwordx2 s[30:31], s[2:3], 0x120
	s_waitcnt lgkmcnt(0)
	v_add_f32_e32 v34, v32, v33
	v_lshlrev_b64 v[32:33], 8, v[142:143]
	v_lshl_add_u64 v[32:33], s[30:31], 0, v[32:33]
	v_lshl_add_u64 v[32:33], s[26:27], 2, v[32:33]
	v_lshl_add_u64 v[32:33], v[32:33], 0, v[136:137]
	global_store_dword v[32:33], v34, off
.LBB0_1147:
	s_or_b64 exec, exec, s[28:29]
	v_or_b32_e32 v140, 16, v142
	v_ashrrev_i32_e32 v141, 31, v140
	v_lshlrev_b64 v[146:147], 14, v[140:141]
	s_waitcnt lgkmcnt(0)
	v_lshl_add_u64 v[32:33], s[10:11], 0, v[146:147]
	v_lshl_add_u64 v[40:41], v[32:33], 0, v[144:145]
	global_load_dwordx4 v[32:35], v[40:41], off nt
	global_load_dwordx4 v[100:103], v[40:41], off offset:64 nt
	global_load_dwordx4 v[154:157], v[40:41], off offset:512 nt
	global_load_dwordx4 v[158:161], v[40:41], off offset:576 nt
	s_waitcnt vmcnt(3)
	v_pk_add_f32 v[40:41], v[8:9], v[32:33]
	s_waitcnt vmcnt(2)
	v_pk_add_f32 v[32:33], v[16:17], v[100:101]
	s_waitcnt vmcnt(1)
	v_pk_add_f32 v[16:17], v[56:57], v[154:155]
	s_waitcnt vmcnt(0)
	v_pk_add_f32 v[8:9], v[48:49], v[158:159]
	v_mul_f32_e32 v48, v41, v41
	v_mul_f32_e32 v49, v33, v33
	v_pk_add_f32 v[42:43], v[10:11], v[34:35]
	v_pk_add_f32 v[34:35], v[18:19], v[102:103]
	v_pk_add_f32 v[10:11], v[50:51], v[160:161]
	v_mul_f32_e32 v50, v17, v17
	v_fmac_f32_e32 v48, v40, v40
	v_fmac_f32_e32 v49, v32, v32
	v_pk_add_f32 v[18:19], v[58:59], v[156:157]
	v_mul_f32_e32 v51, v9, v9
	v_fmac_f32_e32 v50, v16, v16
	v_fmac_f32_e32 v48, v42, v42
	v_fmac_f32_e32 v49, v34, v34
	v_fmac_f32_e32 v51, v8, v8
	v_fmac_f32_e32 v50, v18, v18
	v_fmac_f32_e32 v48, v43, v43
	v_fmac_f32_e32 v49, v35, v35
	v_fmac_f32_e32 v51, v10, v10
	v_fmac_f32_e32 v50, v19, v19
	v_add_f32_e32 v48, v48, v49
	v_add_f32_e32 v48, v48, v50
	v_fmac_f32_e32 v51, v11, v11
	v_add_f32_e32 v56, v48, v51
	ds_bpermute_b32 v57, v153, v56
	v_lshl_add_u64 v[48:49], s[6:7], 0, v[146:147]
	v_lshl_add_u64 v[50:51], v[48:49], 0, v[144:145]
	global_store_dwordx4 v[50:51], v[40:43], off
	global_store_dwordx4 v[50:51], v[32:35], off offset:64
	global_store_dwordx4 v[50:51], v[16:19], off offset:512
	global_store_dwordx4 v[50:51], v[8:11], off offset:576
	s_waitcnt lgkmcnt(0)
	v_add_f32_e32 v48, v56, v57
	ds_bpermute_b32 v49, v152, v48
	s_and_saveexec_b64 s[28:29], vcc
	s_cbranch_execz .LBB0_1149
	s_load_dwordx2 s[30:31], s[2:3], 0x120
	s_waitcnt lgkmcnt(0)
	v_add_f32_e32 v50, v48, v49
	v_lshlrev_b64 v[48:49], 8, v[140:141]
	v_lshl_add_u64 v[48:49], s[30:31], 0, v[48:49]
	v_lshl_add_u64 v[48:49], s[26:27], 2, v[48:49]
	v_lshl_add_u64 v[48:49], v[48:49], 0, v[136:137]
	global_store_dword v[48:49], v50, off
;     ...
;     for (int ai = 0; ai < 2; ++ai)
; #pragma unroll
;       for (int m = 0; m < 4; ++m) {
;         const int row = brow + ai * HALF + wr * 64 + m * 16 + fr;
;         float ssq = 0.f;
; #pragma unroll
;         for (int bj = 0; bj < 2; ++bj)
; #pragma unroll
;           for (int n = 0; n < 2; ++n) {
;             const int col = bcol + bj * HALF + wc * 32 + n * 16 + fq * 4;
;             f32x4 v = acc[ai][bj][m][n];
;             v += *(const f32x4*)(res + (long)row * D + col);
;             if (EPI == 7) *(f32x4*)(outf + (long)row * D + col) = v;
;             acc[ai][bj][m][n] = v;
;             ssq += v[0] * v[0] + v[1] * v[1] + v[2] * v[2] + v[3] * v[3];
;           }
;         ssq += bperm(ssq, lane ^ 16);
;         ssq += bperm(ssq, lane ^ 32);
;         if (fq == 0) p->sspart[(long)row * 64 + pn_ * 4 + wc] = ssq;
.LBB0_1149:
	s_or_b64 exec, exec, s[28:29]
	v_or_b32_e32 v140, 32, v142
	v_ashrrev_i32_e32 v141, 31, v140
	v_lshlrev_b64 v[146:147], 14, v[140:141]
	s_waitcnt lgkmcnt(0)
	v_lshl_add_u64 v[48:49], s[10:11], 0, v[146:147]
	v_lshl_add_u64 v[56:57], v[48:49], 0, v[144:145]
	global_load_dwordx4 v[48:51], v[56:57], off nt
	global_load_dwordx4 v[100:103], v[56:57], off offset:64 nt
	global_load_dwordx4 v[154:157], v[56:57], off offset:512 nt
	global_load_dwordx4 v[158:161], v[56:57], off offset:576 nt
	s_waitcnt vmcnt(3)
	v_pk_add_f32 v[56:57], v[20:21], v[48:49]
	s_waitcnt vmcnt(2)
	v_pk_add_f32 v[48:49], v[28:29], v[100:101]
	s_waitcnt vmcnt(1)
	v_pk_add_f32 v[28:29], v[72:73], v[154:155]
	s_waitcnt vmcnt(0)
	v_pk_add_f32 v[20:21], v[64:65], v[158:159]
	v_mul_f32_e32 v64, v57, v57
	v_mul_f32_e32 v65, v49, v49
	v_pk_add_f32 v[58:59], v[22:23], v[50:51]
	v_pk_add_f32 v[50:51], v[30:31], v[102:103]
	v_pk_add_f32 v[22:23], v[66:67], v[160:161]
	v_mul_f32_e32 v66, v29, v29
	v_fmac_f32_e32 v64, v56, v56
	v_fmac_f32_e32 v65, v48, v48
	v_pk_add_f32 v[30:31], v[74:75], v[156:157]
	v_mul_f32_e32 v67, v21, v21
	v_fmac_f32_e32 v66, v28, v28
	v_fmac_f32_e32 v64, v58, v58
	v_fmac_f32_e32 v65, v50, v50
	v_fmac_f32_e32 v67, v20, v20
	v_fmac_f32_e32 v66, v30, v30
	v_fmac_f32_e32 v64, v59, v59
	v_fmac_f32_e32 v65, v51, v51
	v_fmac_f32_e32 v67, v22, v22
	v_fmac_f32_e32 v66, v31, v31
	v_add_f32_e32 v64, v64, v65
	v_add_f32_e32 v64, v64, v66
	v_fmac_f32_e32 v67, v23, v23
	v_add_f32_e32 v72, v64, v67
	ds_bpermute_b32 v73, v153, v72
	v_lshl_add_u64 v[64:65], s[6:7], 0, v[146:147]
	v_lshl_add_u64 v[66:67], v[64:65], 0, v[144:145]
	global_store_dwordx4 v[66:67], v[56:59], off
	global_store_dwordx4 v[66:67], v[48:51], off offset:64
	global_store_dwordx4 v[66:67], v[28:31], off offset:512
	global_store_dwordx4 v[66:67], v[20:23], off offset:576
	s_waitcnt lgkmcnt(0)
	v_add_f32_e32 v64, v72, v73
	ds_bpermute_b32 v65, v152, v64
	s_and_saveexec_b64 s[28:29], vcc
	s_cbranch_execz .LBB0_1151
	s_load_dwordx2 s[30:31], s[2:3], 0x120
	s_waitcnt lgkmcnt(0)
	v_add_f32_e32 v66, v64, v65
	v_lshlrev_b64 v[64:65], 8, v[140:141]
	v_lshl_add_u64 v[64:65], s[30:31], 0, v[64:65]
	v_lshl_add_u64 v[64:65], s[26:27], 2, v[64:65]
	v_lshl_add_u64 v[64:65], v[64:65], 0, v[136:137]
	global_store_dword v[64:65], v66, off
.LBB0_1151:
	s_or_b64 exec, exec, s[28:29]
	v_or_b32_e32 v140, 48, v142
	v_ashrrev_i32_e32 v141, 31, v140
	v_lshlrev_b64 v[146:147], 14, v[140:141]
	s_waitcnt lgkmcnt(0)
	v_lshl_add_u64 v[64:65], s[10:11], 0, v[146:147]
	v_lshl_add_u64 v[72:73], v[64:65], 0, v[144:145]
	global_load_dwordx4 v[64:67], v[72:73], off nt
	global_load_dwordx4 v[100:103], v[72:73], off offset:64 nt
	global_load_dwordx4 v[154:157], v[72:73], off offset:512 nt
	global_load_dwordx4 v[158:161], v[72:73], off offset:576 nt
	s_waitcnt vmcnt(3)
	v_pk_add_f32 v[72:73], v[36:37], v[64:65]
	s_waitcnt vmcnt(2)
	v_pk_add_f32 v[64:65], v[44:45], v[100:101]
	s_waitcnt vmcnt(1)
	v_pk_add_f32 v[44:45], v[88:89], v[154:155]
	s_waitcnt vmcnt(0)
	v_pk_add_f32 v[36:37], v[76:77], v[158:159]
	v_mul_f32_e32 v76, v73, v73
	v_mul_f32_e32 v77, v65, v65
	v_pk_add_f32 v[74:75], v[38:39], v[66:67]
	v_pk_add_f32 v[66:67], v[46:47], v[102:103]
	v_pk_add_f32 v[38:39], v[78:79], v[160:161]
	v_mul_f32_e32 v78, v45, v45
	v_fmac_f32_e32 v76, v72, v72
	v_fmac_f32_e32 v77, v64, v64
	v_pk_add_f32 v[46:47], v[90:91], v[156:157]
	v_mul_f32_e32 v79, v37, v37
	v_fmac_f32_e32 v78, v44, v44
	v_fmac_f32_e32 v76, v74, v74
	v_fmac_f32_e32 v77, v66, v66
	v_fmac_f32_e32 v79, v36, v36
	v_fmac_f32_e32 v78, v46, v46
	v_fmac_f32_e32 v76, v75, v75
	v_fmac_f32_e32 v77, v67, v67
	v_fmac_f32_e32 v79, v38, v38
	v_fmac_f32_e32 v78, v47, v47
	v_add_f32_e32 v76, v76, v77
	v_add_f32_e32 v76, v76, v78
	v_fmac_f32_e32 v79, v39, v39
	v_add_f32_e32 v88, v76, v79
	ds_bpermute_b32 v89, v153, v88
	v_lshl_add_u64 v[76:77], s[6:7], 0, v[146:147]
	v_lshl_add_u64 v[78:79], v[76:77], 0, v[144:145]
	global_store_dwordx4 v[78:79], v[72:75], off
	global_store_dwordx4 v[78:79], v[64:67], off offset:64
	global_store_dwordx4 v[78:79], v[44:47], off offset:512
	global_store_dwordx4 v[78:79], v[36:39], off offset:576
	s_waitcnt lgkmcnt(0)
	v_add_f32_e32 v76, v88, v89
	ds_bpermute_b32 v77, v152, v76
	s_and_saveexec_b64 s[28:29], vcc
	s_cbranch_execz .LBB0_1153
	s_load_dwordx2 s[30:31], s[2:3], 0x120
	s_waitcnt lgkmcnt(0)
	v_add_f32_e32 v78, v76, v77
	v_lshlrev_b64 v[76:77], 8, v[140:141]
	v_lshl_add_u64 v[76:77], s[30:31], 0, v[76:77]
	v_lshl_add_u64 v[76:77], s[26:27], 2, v[76:77]
	v_lshl_add_u64 v[76:77], v[76:77], 0, v[136:137]
	global_store_dword v[76:77], v78, off
;     ...
;     for (int ai = 0; ai < 2; ++ai)
; #pragma unroll
;       for (int m = 0; m < 4; ++m) {
;         const int row = brow + ai * HALF + wr * 64 + m * 16 + fr;
;         float ssq = 0.f;
; #pragma unroll
;         for (int bj = 0; bj < 2; ++bj)
; #pragma unroll
;           for (int n = 0; n < 2; ++n) {
;             const int col = bcol + bj * HALF + wc * 32 + n * 16 + fq * 4;
;             f32x4 v = acc[ai][bj][m][n];
;             v += *(const f32x4*)(res + (long)row * D + col);
;             if (EPI == 7) *(f32x4*)(outf + (long)row * D + col) = v;
;             acc[ai][bj][m][n] = v;
;             ssq += v[0] * v[0] + v[1] * v[1] + v[2] * v[2] + v[3] * v[3];
;           }
;         ssq += bperm(ssq, lane ^ 16);
;         ssq += bperm(ssq, lane ^ 32);
;         if (fq == 0) p->sspart[(long)row * 64 + pn_ * 4 + wc] = ssq;
.LBB0_1153:
	s_or_b64 exec, exec, s[28:29]
	v_add_u32_e32 v140, 0x80, v142
	v_ashrrev_i32_e32 v141, 31, v140
	v_lshlrev_b64 v[146:147], 14, v[140:141]
	s_waitcnt lgkmcnt(0)
	v_lshl_add_u64 v[76:77], s[10:11], 0, v[146:147]
	v_lshl_add_u64 v[88:89], v[76:77], 0, v[144:145]
	global_load_dwordx4 v[76:79], v[88:89], off nt
	global_load_dwordx4 v[100:103], v[88:89], off offset:64 nt
	global_load_dwordx4 v[154:157], v[88:89], off offset:512 nt
	global_load_dwordx4 v[158:161], v[88:89], off offset:576 nt
	s_waitcnt vmcnt(3)
	v_pk_add_f32 v[88:89], v[52:53], v[76:77]
	s_waitcnt vmcnt(2)
	v_pk_add_f32 v[76:77], v[60:61], v[100:101]
	s_waitcnt vmcnt(1)
	v_pk_add_f32 v[60:61], v[104:105], v[154:155]
	s_waitcnt vmcnt(0)
	v_pk_add_f32 v[52:53], v[96:97], v[158:159]
	v_mul_f32_e32 v96, v89, v89
	v_mul_f32_e32 v97, v77, v77
	v_pk_add_f32 v[90:91], v[54:55], v[78:79]
	v_pk_add_f32 v[78:79], v[62:63], v[102:103]
	v_pk_add_f32 v[54:55], v[98:99], v[160:161]
	v_mul_f32_e32 v98, v61, v61
	v_fmac_f32_e32 v96, v88, v88
	v_fmac_f32_e32 v97, v76, v76
	v_pk_add_f32 v[62:63], v[106:107], v[156:157]
	v_mul_f32_e32 v99, v53, v53
	v_fmac_f32_e32 v98, v60, v60
	v_fmac_f32_e32 v96, v90, v90
	v_fmac_f32_e32 v97, v78, v78
	v_fmac_f32_e32 v99, v52, v52
	v_fmac_f32_e32 v98, v62, v62
	v_fmac_f32_e32 v96, v91, v91
	v_fmac_f32_e32 v97, v79, v79
	v_fmac_f32_e32 v99, v54, v54
	v_fmac_f32_e32 v98, v63, v63
	v_add_f32_e32 v96, v96, v97
	v_add_f32_e32 v96, v96, v98
	v_fmac_f32_e32 v99, v55, v55
	v_add_f32_e32 v100, v96, v99
	ds_bpermute_b32 v101, v153, v100
	v_lshl_add_u64 v[96:97], s[6:7], 0, v[146:147]
	v_lshl_add_u64 v[98:99], v[96:97], 0, v[144:145]
	global_store_dwordx4 v[98:99], v[88:91], off
	global_store_dwordx4 v[98:99], v[76:79], off offset:64
	global_store_dwordx4 v[98:99], v[60:63], off offset:512
	global_store_dwordx4 v[98:99], v[52:55], off offset:576
	s_waitcnt lgkmcnt(0)
	v_add_f32_e32 v96, v100, v101
	ds_bpermute_b32 v97, v152, v96
	s_and_saveexec_b64 s[28:29], vcc
	s_cbranch_execz .LBB0_1155
	s_load_dwordx2 s[30:31], s[2:3], 0x120
	s_waitcnt lgkmcnt(0)
	v_add_f32_e32 v98, v96, v97
	v_lshlrev_b64 v[96:97], 8, v[140:141]
	v_lshl_add_u64 v[96:97], s[30:31], 0, v[96:97]
	v_lshl_add_u64 v[96:97], s[26:27], 2, v[96:97]
	v_lshl_add_u64 v[96:97], v[96:97], 0, v[136:137]
	global_store_dword v[96:97], v98, off
.LBB0_1155:
	s_or_b64 exec, exec, s[28:29]
	v_add_u32_e32 v140, 0x90, v142
	v_ashrrev_i32_e32 v141, 31, v140
	v_lshlrev_b64 v[146:147], 14, v[140:141]
	s_waitcnt lgkmcnt(0)
	v_lshl_add_u64 v[96:97], s[10:11], 0, v[146:147]
	v_lshl_add_u64 v[104:105], v[96:97], 0, v[144:145]
	global_load_dwordx4 v[96:99], v[104:105], off nt
	global_load_dwordx4 v[100:103], v[104:105], off offset:64 nt
	global_load_dwordx4 v[154:157], v[104:105], off offset:512 nt
	global_load_dwordx4 v[158:161], v[104:105], off offset:576 nt
	s_waitcnt vmcnt(3)
	v_pk_add_f32 v[104:105], v[68:69], v[96:97]
	s_waitcnt vmcnt(2)
	v_pk_add_f32 v[96:97], v[80:81], v[100:101]
	s_waitcnt vmcnt(1)
	v_pk_add_f32 v[80:81], v[116:117], v[154:155]
	v_mul_f32_e32 v100, v105, v105
	v_mul_f32_e32 v101, v97, v97
	v_pk_add_f32 v[106:107], v[70:71], v[98:99]
	v_pk_add_f32 v[98:99], v[82:83], v[102:103]
	s_waitcnt vmcnt(0)
	v_pk_add_f32 v[68:69], v[108:109], v[158:159]
	v_mul_f32_e32 v102, v81, v81
	v_fmac_f32_e32 v100, v104, v104
	v_fmac_f32_e32 v101, v96, v96
	v_pk_add_f32 v[82:83], v[118:119], v[156:157]
	v_mul_f32_e32 v103, v69, v69
	v_fmac_f32_e32 v102, v80, v80
	v_fmac_f32_e32 v100, v106, v106
	v_fmac_f32_e32 v101, v98, v98
	v_pk_add_f32 v[70:71], v[110:111], v[160:161]
	v_fmac_f32_e32 v103, v68, v68
	v_fmac_f32_e32 v102, v82, v82
	v_fmac_f32_e32 v100, v107, v107
	v_fmac_f32_e32 v101, v99, v99
	v_fmac_f32_e32 v103, v70, v70
	v_fmac_f32_e32 v102, v83, v83
	v_add_f32_e32 v100, v100, v101
	v_add_f32_e32 v100, v100, v102
	v_fmac_f32_e32 v103, v71, v71
	v_add_f32_e32 v102, v100, v103
	ds_bpermute_b32 v103, v153, v102
	v_lshl_add_u64 v[100:101], s[6:7], 0, v[146:147]
	v_lshl_add_u64 v[100:101], v[100:101], 0, v[144:145]
	global_store_dwordx4 v[100:101], v[104:107], off
	global_store_dwordx4 v[100:101], v[96:99], off offset:64
	global_store_dwordx4 v[100:101], v[80:83], off offset:512
	global_store_dwordx4 v[100:101], v[68:71], off offset:576
	s_waitcnt lgkmcnt(0)
	v_add_f32_e32 v108, v102, v103
	ds_bpermute_b32 v109, v152, v108
	s_and_saveexec_b64 s[28:29], vcc
	s_cbranch_execz .LBB0_1157
	s_load_dwordx2 s[30:31], s[2:3], 0x120
	v_lshlrev_b64 v[100:101], 8, v[140:141]
	s_waitcnt lgkmcnt(0)
	v_add_f32_e32 v102, v108, v109
	v_lshl_add_u64 v[100:101], s[30:31], 0, v[100:101]
	v_lshl_add_u64 v[100:101], s[26:27], 2, v[100:101]
	v_lshl_add_u64 v[100:101], v[100:101], 0, v[136:137]
	global_store_dword v[100:101], v102, off
;     ...
;     for (int ai = 0; ai < 2; ++ai)
; #pragma unroll
;       for (int m = 0; m < 4; ++m) {
;         const int row = brow + ai * HALF + wr * 64 + m * 16 + fr;
;         float ssq = 0.f;
; #pragma unroll
;         for (int bj = 0; bj < 2; ++bj)
; #pragma unroll
;           for (int n = 0; n < 2; ++n) {
;             const int col = bcol + bj * HALF + wc * 32 + n * 16 + fq * 4;
;             f32x4 v = acc[ai][bj][m][n];
;             v += *(const f32x4*)(res + (long)row * D + col);
;             if (EPI == 7) *(f32x4*)(outf + (long)row * D + col) = v;
;             acc[ai][bj][m][n] = v;
;             ssq += v[0] * v[0] + v[1] * v[1] + v[2] * v[2] + v[3] * v[3];
;           }
;         ssq += bperm(ssq, lane ^ 16);
;         ssq += bperm(ssq, lane ^ 32);
;         if (fq == 0) p->sspart[(long)row * 64 + pn_ * 4 + wc] = ssq;
.LBB0_1157:
	s_or_b64 exec, exec, s[28:29]
	v_add_u32_e32 v146, 0xa0, v142
	v_ashrrev_i32_e32 v147, 31, v146
	v_lshlrev_b64 v[162:163], 14, v[146:147]
	v_lshl_add_u64 v[100:101], s[10:11], 0, v[162:163]
	v_lshl_add_u64 v[116:117], v[100:101], 0, v[144:145]
	global_load_dwordx4 v[100:103], v[116:117], off nt
	s_waitcnt lgkmcnt(0)
	global_load_dwordx4 v[108:111], v[116:117], off offset:64 nt
	global_load_dwordx4 v[154:157], v[116:117], off offset:512 nt
	global_load_dwordx4 v[158:161], v[116:117], off offset:576 nt
	s_waitcnt vmcnt(3)
	v_pk_add_f32 v[116:117], v[84:85], v[100:101]
	s_waitcnt vmcnt(2)
	v_pk_add_f32 v[108:109], v[92:93], v[108:109]
	s_waitcnt vmcnt(1)
	v_pk_add_f32 v[92:93], v[124:125], v[154:155]
	v_mul_f32_e32 v100, v117, v117
	v_mul_f32_e32 v101, v109, v109
	v_pk_add_f32 v[118:119], v[86:87], v[102:103]
	v_pk_add_f32 v[110:111], v[94:95], v[110:111]
	s_waitcnt vmcnt(0)
	v_pk_add_f32 v[84:85], v[120:121], v[158:159]
	v_mul_f32_e32 v102, v93, v93
	v_fmac_f32_e32 v100, v116, v116
	v_fmac_f32_e32 v101, v108, v108
	v_pk_add_f32 v[94:95], v[126:127], v[156:157]
	v_mul_f32_e32 v103, v85, v85
	v_fmac_f32_e32 v102, v92, v92
	v_fmac_f32_e32 v100, v118, v118
	v_fmac_f32_e32 v101, v110, v110
	v_pk_add_f32 v[86:87], v[122:123], v[160:161]
	v_fmac_f32_e32 v103, v84, v84
	v_fmac_f32_e32 v102, v94, v94
	v_fmac_f32_e32 v100, v119, v119
	v_fmac_f32_e32 v101, v111, v111
	v_fmac_f32_e32 v103, v86, v86
	v_fmac_f32_e32 v102, v95, v95
	v_add_f32_e32 v100, v100, v101
	v_add_f32_e32 v100, v100, v102
	v_fmac_f32_e32 v103, v87, v87
	v_add_f32_e32 v102, v100, v103
	ds_bpermute_b32 v103, v153, v102
	v_lshl_add_u64 v[100:101], s[6:7], 0, v[162:163]
	v_lshl_add_u64 v[100:101], v[100:101], 0, v[144:145]
	global_store_dwordx4 v[100:101], v[116:119], off
	global_store_dwordx4 v[100:101], v[108:111], off offset:64
	global_store_dwordx4 v[100:101], v[92:95], off offset:512
	global_store_dwordx4 v[100:101], v[84:87], off offset:576
	s_waitcnt lgkmcnt(0)
	v_add_f32_e32 v120, v102, v103
	ds_bpermute_b32 v121, v152, v120
	s_and_saveexec_b64 s[28:29], vcc
	s_cbranch_execz .LBB0_1159
	s_load_dwordx2 s[30:31], s[2:3], 0x120
	v_lshlrev_b64 v[100:101], 8, v[146:147]
	s_waitcnt lgkmcnt(0)
	v_add_f32_e32 v102, v120, v121
	v_lshl_add_u64 v[100:101], s[30:31], 0, v[100:101]
	v_lshl_add_u64 v[100:101], s[26:27], 2, v[100:101]
	v_lshl_add_u64 v[100:101], v[100:101], 0, v[136:137]
	global_store_dword v[100:101], v102, off
.LBB0_1159:
	s_or_b64 exec, exec, s[28:29]
	v_add_u32_e32 v142, 0xb0, v142
	v_ashrrev_i32_e32 v143, 31, v142
	v_lshlrev_b64 v[146:147], 14, v[142:143]
	v_lshl_add_u64 v[100:101], s[10:11], 0, v[146:147]
	v_lshl_add_u64 v[124:125], v[100:101], 0, v[144:145]
	global_load_dwordx4 v[100:103], v[124:125], off nt
	s_waitcnt lgkmcnt(0)
	global_load_dwordx4 v[120:123], v[124:125], off offset:64 nt
	global_load_dwordx4 v[154:157], v[124:125], off offset:512 nt
	global_load_dwordx4 v[158:161], v[124:125], off offset:576 nt
	s_waitcnt vmcnt(3)
	v_pk_add_f32 v[124:125], v[174:175], v[100:101]
	s_waitcnt vmcnt(2)
	v_pk_add_f32 v[120:121], v[112:113], v[120:121]
	s_waitcnt vmcnt(1)
	v_pk_add_f32 v[112:113], v[132:133], v[154:155]
	s_waitcnt vmcnt(0)
	v_pk_add_f32 v[100:101], v[128:129], v[158:159]
	v_mul_f32_e32 v128, v125, v125
	v_mul_f32_e32 v129, v121, v121
	v_pk_add_f32 v[126:127], v[176:177], v[102:103]
	v_pk_add_f32 v[122:123], v[114:115], v[122:123]
	v_pk_add_f32 v[102:103], v[130:131], v[160:161]
	v_mul_f32_e32 v130, v113, v113
	v_fmac_f32_e32 v128, v124, v124
	v_fmac_f32_e32 v129, v120, v120
	v_pk_add_f32 v[114:115], v[134:135], v[156:157]
	v_mul_f32_e32 v131, v101, v101
	v_fmac_f32_e32 v130, v112, v112
	v_fmac_f32_e32 v128, v126, v126
	v_fmac_f32_e32 v129, v122, v122
	v_fmac_f32_e32 v131, v100, v100
	v_fmac_f32_e32 v130, v114, v114
	v_fmac_f32_e32 v128, v127, v127
	v_fmac_f32_e32 v129, v123, v123
	v_fmac_f32_e32 v131, v102, v102
	v_fmac_f32_e32 v130, v115, v115
	v_add_f32_e32 v128, v128, v129
	v_add_f32_e32 v128, v128, v130
	v_fmac_f32_e32 v131, v103, v103
	v_add_f32_e32 v132, v128, v131
	ds_bpermute_b32 v133, v153, v132
	v_lshl_add_u64 v[128:129], s[6:7], 0, v[146:147]
	v_lshl_add_u64 v[130:131], v[128:129], 0, v[144:145]
	global_store_dwordx4 v[130:131], v[124:127], off
	global_store_dwordx4 v[130:131], v[120:123], off offset:64
	global_store_dwordx4 v[130:131], v[112:115], off offset:512
	global_store_dwordx4 v[130:131], v[100:103], off offset:576
	s_waitcnt lgkmcnt(0)
	v_add_f32_e32 v128, v132, v133
	ds_bpermute_b32 v129, v152, v128
	s_and_saveexec_b64 s[28:29], vcc
	s_cbranch_execz .LBB0_1161
	s_load_dwordx2 s[30:31], s[2:3], 0x120
	s_waitcnt lgkmcnt(0)
	v_add_f32_e32 v130, v128, v129
	v_lshlrev_b64 v[128:129], 8, v[142:143]
	v_lshl_add_u64 v[128:129], s[30:31], 0, v[128:129]
	v_lshl_add_u64 v[128:129], s[26:27], 2, v[128:129]
	v_lshl_add_u64 v[128:129], v[128:129], 0, v[136:137]
	global_store_dword v[128:129], v130, off

; #define tidx() tidx_(wv)
; __device__ __forceinline__ void transpose_tile(const float* __restrict__ W, bf16* __restrict__ Wt, int K, int N,
;                                                int k0, int n0, float* tile, int wv) {
;   const int tid = tidx();
;   const int r = tid >> 6, c4 = tid & 63;
;   const int n = n0 + c4 * 4;
;   float4 v[8];
; #pragma unroll
;   for (int i = 0; i < 8; ++i) {
;     if (n < N) v[i] = *(const float4*)(W + (long)(k0 + r + 8 * i) * N + n);
;     else v[i] = make_float4(0.f, 0.f, 0.f, 0.f);
;   }
; #pragma unroll
;   for (int i = 0; i < 8; ++i) {
;     float* d = tile + (r + 8 * i) * 257 + c4 * 4;
;     d[0] = v[i].x; d[1] = v[i].y; d[2] = v[i].z; d[3] = v[i].w;
;   }
;   __syncthreads();
;   const int k8 = tid & 7;
; #pragma unroll
;   for (int i = 0; i < 4; ++i) {
;     int nl = (tid >> 3) + 64 * i;
;     if (n0 + nl < N) {
;       bf16x8 o;
; #pragma unroll
;       for (int j = 0; j < 8; ++j) o[j] = (short)f2bf(tile[(k8 * 8 + j) * 257 + nl]);
;       *(bf16x8*)(Wt + (long)(n0 + nl) * K + k0 + k8 * 8) = o;
;     }
;   }
;   __syncthreads();
.LBB0_1220:
	v_readlane_b32 s13, v253, 3
	v_mbcnt_lo_u32_b32 v32, -1, 0
	v_mbcnt_hi_u32_b32 v32, -1, v32
	s_and_b32 s12, s7, 0xffffffc0
	v_lshlrev_b32_e32 v0, 2, v32
	v_or_b32_e32 v33, s13, v32
	s_and_b32 s15, s10, 0xf00
	v_ashrrev_i32_e32 v34, 6, v33
	v_and_b32_e32 v35, 0xfc, v0
	v_or_b32_e32 v1, s15, v35
	v_add_u32_e32 v0, s12, v34
	v_lshlrev_b32_e32 v148, 2, v1
	v_ashrrev_i32_e32 v1, 31, v0
	s_waitcnt lgkmcnt(0)
	v_lshl_add_u64 v[2:3], s[4:5], 0, v[148:149]
	v_lshlrev_b64 v[0:1], 14, v[0:1]
	v_lshl_add_u64 v[28:29], v[2:3], 0, v[0:1]
	v_add_co_u32_e32 v4, vcc, s71, v28
	s_ashr_i32 s13, s12, 31
	s_nop 0
	v_addc_co_u32_e32 v5, vcc, 0, v29, vcc
	v_add_co_u32_e32 v8, vcc, s72, v28
	global_load_dwordx4 v[0:3], v[28:29], off nt
	s_nop 0
	global_load_dwordx4 v[4:7], v[4:5], off nt
	v_addc_co_u32_e32 v9, vcc, 0, v29, vcc
	v_add_co_u32_e32 v12, vcc, s73, v28
	v_lshlrev_b32_e32 v32, 3, v32
	s_nop 0
	v_addc_co_u32_e32 v13, vcc, 0, v29, vcc
	v_add_co_u32_e32 v16, vcc, s74, v28
	global_load_dwordx4 v[8:11], v[8:9], off nt
	s_nop 0
	global_load_dwordx4 v[12:15], v[12:13], off nt
	v_addc_co_u32_e32 v17, vcc, 0, v29, vcc
	v_add_co_u32_e32 v20, vcc, s75, v28
	v_lshlrev_b32_e32 v35, 2, v35
	s_nop 0
	v_addc_co_u32_e32 v21, vcc, 0, v29, vcc
	global_load_dwordx4 v[16:19], v[16:17], off nt
	s_nop 0
	global_load_dwordx4 v[20:23], v[20:21], off nt
	v_add_co_u32_e32 v24, vcc, s76, v28
	v_mul_lo_u32 v34, v34, s70
	s_nop 0
	v_addc_co_u32_e32 v25, vcc, 0, v29, vcc
	global_load_dwordx4 v[24:27], v[24:25], off nt
	v_add_co_u32_e32 v28, vcc, s77, v28
	s_lshl_b64 s[12:13], s[12:13], 1
	s_nop 0
	v_addc_co_u32_e32 v29, vcc, 0, v29, vcc
	global_load_dwordx4 v[28:31], v[28:29], off nt
	v_ashrrev_i32_e32 v33, 3, v33
	v_and_b32_e32 v32, 56, v32
	v_add3_u32 v34, 0, v35, v34
	s_add_u32 s12, s8, s12
	v_add_u32_e32 v35, 0x2020, v34
	v_add_u32_e32 v36, 0x2028, v34
	v_add_u32_e32 v37, 0x4040, v34
	v_add_u32_e32 v38, 0x4048, v34
	v_add_u32_e32 v39, 0x6060, v34
	v_add_u32_e32 v40, 0x6068, v34
	v_add_u32_e32 v41, 0x8080, v34
	v_add_u32_e32 v42, 0x8088, v34
	v_add_u32_e32 v43, 0xa0a0, v34
	v_add_u32_e32 v44, 0xa0a8, v34
	v_add_u32_e32 v45, 0xc0c0, v34
	v_add_u32_e32 v46, 0xc0c8, v34
	v_add_u32_e32 v47, 0xe0e0, v34
	v_add_u32_e32 v48, 0xe0e8, v34
	s_addc_u32 s13, s9, s13
	v_lshlrev_b32_e32 v148, 1, v32
	s_waitcnt vmcnt(0)
	ds_write2_b32 v34, v0, v1 offset1:1
	ds_write2_b32 v34, v2, v3 offset0:2 offset1:3
	ds_write2_b32 v35, v4, v5 offset1:1
	ds_write2_b32 v36, v6, v7 offset1:1
	ds_write2_b32 v37, v8, v9 offset1:1
	ds_write2_b32 v38, v10, v11 offset1:1
	ds_write2_b32 v39, v12, v13 offset1:1
	ds_write2_b32 v40, v14, v15 offset1:1
	ds_write2_b32 v41, v16, v17 offset1:1
	ds_write2_b32 v42, v18, v19 offset1:1
	ds_write2_b32 v43, v20, v21 offset1:1
	ds_write2_b32 v44, v22, v23 offset1:1
	ds_write2_b32 v45, v24, v25 offset1:1
	ds_write2_b32 v46, v26, v27 offset1:1
	ds_write2_b32 v47, v28, v29 offset1:1
	ds_write2_b32 v48, v30, v31 offset1:1
	v_add_u32_e32 v3, s15, v33
	v_lshlrev_b32_e32 v2, 2, v33
	v_mul_u32_u24_e32 v4, 0x404, v32
	v_lshl_add_u64 v[0:1], s[12:13], 0, v[148:149]
	v_cmp_gt_i32_e32 vcc, s78, v3
	v_add3_u32 v2, 0, v2, v4
	s_waitcnt lgkmcnt(0)
	s_barrier
	s_and_saveexec_b64 s[12:13], vcc
	s_cbranch_execz .LBB0_1222
	ds_read_b32 v4, v2 offset:4112
	ds_read_b32 v5, v2 offset:5140
	ds_read_b32 v6, v2 offset:6168
	ds_read_b32 v7, v2 offset:7196
	ds_read_b32 v8, v2
	ds_read_b32 v9, v2 offset:1028
	ds_read_b32 v10, v2 offset:2056
	ds_read_b32 v11, v2 offset:3084
	s_waitcnt lgkmcnt(4)
	v_bfe_u32 v12, v7, 16, 1
	v_bfe_u32 v13, v6, 16, 1
	v_bfe_u32 v14, v5, 16, 1
	v_bfe_u32 v15, v4, 16, 1
	s_waitcnt lgkmcnt(0)
	v_bfe_u32 v16, v11, 16, 1
	v_bfe_u32 v17, v10, 16, 1
	v_bfe_u32 v18, v9, 16, 1
	v_bfe_u32 v19, v8, 16, 1
	v_add3_u32 v8, v8, v19, s79
	v_add3_u32 v9, v9, v18, s79
	v_add3_u32 v10, v10, v17, s79
	v_add3_u32 v11, v11, v16, s79
	v_add3_u32 v4, v4, v15, s79
	v_add3_u32 v5, v5, v14, s79
	v_add3_u32 v6, v6, v13, s79
	v_add3_u32 v7, v7, v12, s79
	v_perm_b32 v7, v7, v6, s80
	v_perm_b32 v6, v5, v4, s80
	v_perm_b32 v5, v11, v10, s80
	v_perm_b32 v4, v9, v8, s80
	v_mad_i64_i32 v[8:9], s[40:41], v3, s81, v[0:1]
	global_store_dwordx4 v[8:9], v[4:7], off

;     ...
;     for (int ai = 0; ai < 2; ++ai)
; #pragma unroll
;       for (int m = 0; m < 4; ++m) {
;         const int row = brow + ai * HALF + wr * 64 + m * 16 + fr;
;         float ssq = 0.f;
; #pragma unroll
;         for (int bj = 0; bj < 2; ++bj)
; #pragma unroll
;           for (int n = 0; n < 2; ++n) {
;             const int col = bcol + bj * HALF + wc * 32 + n * 16 + fq * 4;
;             f32x4 v = acc[ai][bj][m][n];
;             v += *(const f32x4*)(res + (long)row * D + col);
;             if (EPI == 7) *(f32x4*)(outf + (long)row * D + col) = v;
;             acc[ai][bj][m][n] = v;
;             ssq += v[0] * v[0] + v[1] * v[1] + v[2] * v[2] + v[3] * v[3];
;           }
;         ssq += bperm(ssq, lane ^ 16);
;         ssq += bperm(ssq, lane ^ 32);
;         if (fq == 0) p->sspart[(long)row * 64 + pn_ * 4 + wc] = ssq;
.LBB0_1338:
	s_or_b64 exec, exec, s[4:5]
	v_or_b32_e32 v128, s34, v142
	v_add_u32_e32 v142, v143, v128
	v_lshrrev_b32_e32 v130, 2, v140
	v_lshlrev_b32_e32 v128, 5, v141
	v_and_b32_e32 v130, 12, v130
	v_ashrrev_i32_e32 v143, 31, v142
	v_or3_b32 v130, v128, v130, s25
	v_lshlrev_b64 v[132:133], 14, v[142:143]
	v_lshl_add_u64 v[132:133], s[8:9], 0, v[132:133]
	v_ashrrev_i32_e32 v131, 31, v130
	v_lshl_add_u64 v[136:137], v[130:131], 2, v[132:133]
	global_load_dwordx4 v[132:135], v[136:137], off nt
	global_load_dwordx4 v[152:155], v[136:137], off offset:64 nt
	global_load_dwordx4 v[156:159], v[136:137], off offset:512 nt
	global_load_dwordx4 v[160:163], v[136:137], off offset:576 nt
	v_and_b32_e32 v128, 63, v140
	v_lshlrev_b32_e32 v140, 2, v128
	v_xor_b32_e32 v150, 64, v140
	v_xor_b32_e32 v151, 0x80, v140
	s_ashr_i32 s4, s24, 1
	s_and_b32 s4, s4, -4
	v_cmp_gt_u32_e32 vcc, 16, v128
	s_ashr_i32 s5, s4, 31
	v_lshlrev_b32_e32 v128, 2, v141
	s_waitcnt vmcnt(0)
	v_pk_add_f32 v[136:137], v[114:115], v[134:135]
	v_pk_add_f32 v[138:139], v[112:113], v[132:133]
	v_pk_add_f32 v[134:135], v[116:117], v[152:153]
	v_pk_add_f32 v[132:133], v[118:119], v[154:155]
	v_pk_add_f32 v[118:119], v[124:125], v[156:157]
	v_pk_add_f32 v[114:115], v[120:121], v[160:161]
	v_mul_f32_e32 v120, v139, v139
	v_mul_f32_e32 v121, v135, v135
	v_pk_add_f32 v[112:113], v[122:123], v[162:163]
	v_mul_f32_e32 v122, v119, v119
	v_fmac_f32_e32 v120, v138, v138
	v_fmac_f32_e32 v121, v134, v134
	v_pk_add_f32 v[116:117], v[126:127], v[158:159]
	v_mul_f32_e32 v123, v115, v115
	v_fmac_f32_e32 v122, v118, v118
	v_fmac_f32_e32 v120, v136, v136
	v_fmac_f32_e32 v121, v132, v132
	v_fmac_f32_e32 v123, v114, v114
	v_fmac_f32_e32 v122, v116, v116
	v_fmac_f32_e32 v120, v137, v137
	v_fmac_f32_e32 v121, v133, v133
	v_fmac_f32_e32 v123, v112, v112
	v_fmac_f32_e32 v122, v117, v117
	v_add_f32_e32 v120, v120, v121
	v_add_f32_e32 v120, v120, v122
	v_fmac_f32_e32 v123, v113, v113
	v_add_f32_e32 v120, v120, v123
	ds_bpermute_b32 v121, v150, v120
	s_waitcnt lgkmcnt(0)
	v_add_f32_e32 v120, v120, v121
	ds_bpermute_b32 v121, v151, v120
	s_and_saveexec_b64 s[6:7], vcc
	s_cbranch_execz .LBB0_1340
	s_load_dwordx2 s[22:23], s[42:43], 0x120
	s_waitcnt lgkmcnt(0)
	v_add_f32_e32 v122, v120, v121
	v_lshlrev_b64 v[120:121], 8, v[142:143]
	v_lshl_add_u64 v[120:121], s[22:23], 0, v[120:121]
	v_lshl_add_u64 v[120:121], s[4:5], 2, v[120:121]
	v_lshl_add_u64 v[120:121], v[120:121], 0, v[128:129]
	global_store_dword v[120:121], v122, off
.LBB0_1340:
	s_or_b64 exec, exec, s[6:7]
	v_or_b32_e32 v140, 16, v142
	v_ashrrev_i32_e32 v141, 31, v140
	s_waitcnt lgkmcnt(0)
	v_lshlrev_b64 v[120:121], 14, v[140:141]
	v_lshl_add_u64 v[120:121], s[8:9], 0, v[120:121]
	v_lshl_add_u64 v[124:125], v[130:131], 2, v[120:121]
	global_load_dwordx4 v[120:123], v[124:125], off nt
	global_load_dwordx4 v[152:155], v[124:125], off offset:64 nt
	global_load_dwordx4 v[156:159], v[124:125], off offset:512 nt
	global_load_dwordx4 v[160:163], v[124:125], off offset:576 nt
	s_waitcnt vmcnt(3)
	v_pk_add_f32 v[124:125], v[98:99], v[122:123]
	v_pk_add_f32 v[126:127], v[96:97], v[120:121]
	s_waitcnt vmcnt(2)
	v_pk_add_f32 v[122:123], v[100:101], v[152:153]
	v_pk_add_f32 v[120:121], v[102:103], v[154:155]
	s_waitcnt vmcnt(1)
	v_pk_add_f32 v[102:103], v[108:109], v[156:157]
	s_waitcnt vmcnt(0)
	v_pk_add_f32 v[98:99], v[104:105], v[160:161]
	v_mul_f32_e32 v104, v127, v127
	v_mul_f32_e32 v105, v123, v123
	v_pk_add_f32 v[96:97], v[106:107], v[162:163]
	v_mul_f32_e32 v106, v103, v103
	v_fmac_f32_e32 v104, v126, v126
	v_fmac_f32_e32 v105, v122, v122
	v_pk_add_f32 v[100:101], v[110:111], v[158:159]
	v_mul_f32_e32 v107, v99, v99
	v_fmac_f32_e32 v106, v102, v102
	v_fmac_f32_e32 v104, v124, v124
	v_fmac_f32_e32 v105, v120, v120
	v_fmac_f32_e32 v107, v98, v98
	v_fmac_f32_e32 v106, v100, v100
	v_fmac_f32_e32 v104, v125, v125
	v_fmac_f32_e32 v105, v121, v121
	v_fmac_f32_e32 v107, v96, v96
	v_fmac_f32_e32 v106, v101, v101
	v_add_f32_e32 v104, v104, v105
	v_add_f32_e32 v104, v104, v106
	v_fmac_f32_e32 v107, v97, v97
	v_add_f32_e32 v104, v104, v107
	ds_bpermute_b32 v105, v150, v104
	s_waitcnt lgkmcnt(0)
	v_add_f32_e32 v104, v104, v105
	ds_bpermute_b32 v105, v151, v104
	s_and_saveexec_b64 s[6:7], vcc
	s_cbranch_execz .LBB0_1342
	s_load_dwordx2 s[22:23], s[42:43], 0x120
	s_waitcnt lgkmcnt(0)
	v_add_f32_e32 v106, v104, v105
	v_lshlrev_b64 v[104:105], 8, v[140:141]
	v_lshl_add_u64 v[104:105], s[22:23], 0, v[104:105]
	v_lshl_add_u64 v[104:105], s[4:5], 2, v[104:105]
	v_lshl_add_u64 v[104:105], v[104:105], 0, v[128:129]
	global_store_dword v[104:105], v106, off
.LBB0_1342:
	s_or_b64 exec, exec, s[6:7]
	v_or_b32_e32 v140, 32, v142
	v_ashrrev_i32_e32 v141, 31, v140
	s_waitcnt lgkmcnt(0)
	v_lshlrev_b64 v[104:105], 14, v[140:141]
	v_lshl_add_u64 v[104:105], s[8:9], 0, v[104:105]
	v_lshl_add_u64 v[108:109], v[130:131], 2, v[104:105]
	global_load_dwordx4 v[104:107], v[108:109], off nt
	global_load_dwordx4 v[152:155], v[108:109], off offset:64 nt
	global_load_dwordx4 v[156:159], v[108:109], off offset:512 nt
	global_load_dwordx4 v[160:163], v[108:109], off offset:576 nt
	s_waitcnt vmcnt(3)
	v_pk_add_f32 v[108:109], v[82:83], v[106:107]
	v_pk_add_f32 v[110:111], v[80:81], v[104:105]
	s_waitcnt vmcnt(2)
	v_pk_add_f32 v[106:107], v[84:85], v[152:153]
	v_pk_add_f32 v[104:105], v[86:87], v[154:155]
	s_waitcnt vmcnt(1)
	v_pk_add_f32 v[86:87], v[92:93], v[156:157]
	s_waitcnt vmcnt(0)
	v_pk_add_f32 v[82:83], v[88:89], v[160:161]
	v_mul_f32_e32 v88, v111, v111
	v_mul_f32_e32 v89, v107, v107
	v_pk_add_f32 v[80:81], v[90:91], v[162:163]
	v_mul_f32_e32 v90, v87, v87
	v_fmac_f32_e32 v88, v110, v110
	v_fmac_f32_e32 v89, v106, v106
	v_pk_add_f32 v[84:85], v[94:95], v[158:159]
	v_mul_f32_e32 v91, v83, v83
	v_fmac_f32_e32 v90, v86, v86
	v_fmac_f32_e32 v88, v108, v108
	v_fmac_f32_e32 v89, v104, v104
	v_fmac_f32_e32 v91, v82, v82
	v_fmac_f32_e32 v90, v84, v84
	v_fmac_f32_e32 v88, v109, v109
	v_fmac_f32_e32 v89, v105, v105
	v_fmac_f32_e32 v91, v80, v80
	v_fmac_f32_e32 v90, v85, v85
	v_add_f32_e32 v88, v88, v89
	v_add_f32_e32 v88, v88, v90
	v_fmac_f32_e32 v91, v81, v81
	v_add_f32_e32 v88, v88, v91
	ds_bpermute_b32 v89, v150, v88
	s_waitcnt lgkmcnt(0)
	v_add_f32_e32 v88, v88, v89
	ds_bpermute_b32 v89, v151, v88
	s_and_saveexec_b64 s[6:7], vcc
	s_cbranch_execz .LBB0_1344
	s_load_dwordx2 s[22:23], s[42:43], 0x120
	s_waitcnt lgkmcnt(0)
	v_add_f32_e32 v90, v88, v89
	v_lshlrev_b64 v[88:89], 8, v[140:141]
	v_lshl_add_u64 v[88:89], s[22:23], 0, v[88:89]
	v_lshl_add_u64 v[88:89], s[4:5], 2, v[88:89]
	v_lshl_add_u64 v[88:89], v[88:89], 0, v[128:129]
	global_store_dword v[88:89], v90, off
;     ...
;     for (int ai = 0; ai < 2; ++ai)
; #pragma unroll
;       for (int m = 0; m < 4; ++m) {
;         const int row = brow + ai * HALF + wr * 64 + m * 16 + fr;
;         float ssq = 0.f;
; #pragma unroll
;         for (int bj = 0; bj < 2; ++bj)
; #pragma unroll
;           for (int n = 0; n < 2; ++n) {
;             const int col = bcol + bj * HALF + wc * 32 + n * 16 + fq * 4;
;             f32x4 v = acc[ai][bj][m][n];
;             v += *(const f32x4*)(res + (long)row * D + col);
;             if (EPI == 7) *(f32x4*)(outf + (long)row * D + col) = v;
;             acc[ai][bj][m][n] = v;
;             ssq += v[0] * v[0] + v[1] * v[1] + v[2] * v[2] + v[3] * v[3];
;           }
;         ssq += bperm(ssq, lane ^ 16);
;         ssq += bperm(ssq, lane ^ 32);
;         if (fq == 0) p->sspart[(long)row * 64 + pn_ * 4 + wc] = ssq;
.LBB0_1344:
	s_or_b64 exec, exec, s[6:7]
	v_or_b32_e32 v140, 48, v142
	v_ashrrev_i32_e32 v141, 31, v140
	s_waitcnt lgkmcnt(0)
	v_lshlrev_b64 v[88:89], 14, v[140:141]
	v_lshl_add_u64 v[88:89], s[8:9], 0, v[88:89]
	v_lshl_add_u64 v[92:93], v[130:131], 2, v[88:89]
	global_load_dwordx4 v[88:91], v[92:93], off nt
	global_load_dwordx4 v[152:155], v[92:93], off offset:64 nt
	global_load_dwordx4 v[156:159], v[92:93], off offset:512 nt
	global_load_dwordx4 v[160:163], v[92:93], off offset:576 nt
	s_waitcnt vmcnt(3)
	v_pk_add_f32 v[92:93], v[66:67], v[90:91]
	v_pk_add_f32 v[94:95], v[64:65], v[88:89]
	s_waitcnt vmcnt(2)
	v_pk_add_f32 v[90:91], v[68:69], v[152:153]
	v_pk_add_f32 v[88:89], v[70:71], v[154:155]
	s_waitcnt vmcnt(1)
	v_pk_add_f32 v[70:71], v[76:77], v[156:157]
	s_waitcnt vmcnt(0)
	v_pk_add_f32 v[66:67], v[72:73], v[160:161]
	v_mul_f32_e32 v72, v95, v95
	v_mul_f32_e32 v73, v91, v91
	v_pk_add_f32 v[64:65], v[74:75], v[162:163]
	v_mul_f32_e32 v74, v71, v71
	v_fmac_f32_e32 v72, v94, v94
	v_fmac_f32_e32 v73, v90, v90
	v_pk_add_f32 v[68:69], v[78:79], v[158:159]
	v_mul_f32_e32 v75, v67, v67
	v_fmac_f32_e32 v74, v70, v70
	v_fmac_f32_e32 v72, v92, v92
	v_fmac_f32_e32 v73, v88, v88
	v_fmac_f32_e32 v75, v66, v66
	v_fmac_f32_e32 v74, v68, v68
	v_fmac_f32_e32 v72, v93, v93
	v_fmac_f32_e32 v73, v89, v89
	v_fmac_f32_e32 v75, v64, v64
	v_fmac_f32_e32 v74, v69, v69
	v_add_f32_e32 v72, v72, v73
	v_add_f32_e32 v72, v72, v74
	v_fmac_f32_e32 v75, v65, v65
	v_add_f32_e32 v72, v72, v75
	ds_bpermute_b32 v73, v150, v72
	s_waitcnt lgkmcnt(0)
	v_add_f32_e32 v72, v72, v73
	ds_bpermute_b32 v73, v151, v72
	s_and_saveexec_b64 s[6:7], vcc
	s_cbranch_execz .LBB0_1346
	s_load_dwordx2 s[22:23], s[42:43], 0x120
	s_waitcnt lgkmcnt(0)
	v_add_f32_e32 v74, v72, v73
	v_lshlrev_b64 v[72:73], 8, v[140:141]
	v_lshl_add_u64 v[72:73], s[22:23], 0, v[72:73]
	v_lshl_add_u64 v[72:73], s[4:5], 2, v[72:73]
	v_lshl_add_u64 v[72:73], v[72:73], 0, v[128:129]
	global_store_dword v[72:73], v74, off
.LBB0_1346:
	s_or_b64 exec, exec, s[6:7]
	v_add_u32_e32 v140, 0x80, v142
	v_ashrrev_i32_e32 v141, 31, v140
	s_waitcnt lgkmcnt(0)
	v_lshlrev_b64 v[72:73], 14, v[140:141]
	v_lshl_add_u64 v[72:73], s[8:9], 0, v[72:73]
	v_lshl_add_u64 v[76:77], v[130:131], 2, v[72:73]
	global_load_dwordx4 v[72:75], v[76:77], off nt
	global_load_dwordx4 v[152:155], v[76:77], off offset:64 nt
	global_load_dwordx4 v[156:159], v[76:77], off offset:512 nt
	global_load_dwordx4 v[160:163], v[76:77], off offset:576 nt
	s_waitcnt vmcnt(3)
	v_pk_add_f32 v[76:77], v[50:51], v[74:75]
	v_pk_add_f32 v[78:79], v[48:49], v[72:73]
	s_waitcnt vmcnt(2)
	v_pk_add_f32 v[74:75], v[52:53], v[152:153]
	v_pk_add_f32 v[72:73], v[54:55], v[154:155]
	s_waitcnt vmcnt(1)
	v_pk_add_f32 v[54:55], v[60:61], v[156:157]
	s_waitcnt vmcnt(0)
	v_pk_add_f32 v[50:51], v[56:57], v[160:161]
	v_mul_f32_e32 v56, v79, v79
	v_mul_f32_e32 v57, v75, v75
	v_pk_add_f32 v[48:49], v[58:59], v[162:163]
	v_mul_f32_e32 v58, v55, v55
	v_fmac_f32_e32 v56, v78, v78
	v_fmac_f32_e32 v57, v74, v74
	v_pk_add_f32 v[52:53], v[62:63], v[158:159]
	v_mul_f32_e32 v59, v51, v51
	v_fmac_f32_e32 v58, v54, v54
	v_fmac_f32_e32 v56, v76, v76
	v_fmac_f32_e32 v57, v72, v72
	v_fmac_f32_e32 v59, v50, v50
	v_fmac_f32_e32 v58, v52, v52
	v_fmac_f32_e32 v56, v77, v77
	v_fmac_f32_e32 v57, v73, v73
	v_fmac_f32_e32 v59, v48, v48
	v_fmac_f32_e32 v58, v53, v53
	v_add_f32_e32 v56, v56, v57
	v_add_f32_e32 v56, v56, v58
	v_fmac_f32_e32 v59, v49, v49
	v_add_f32_e32 v56, v56, v59
	ds_bpermute_b32 v57, v150, v56
	s_waitcnt lgkmcnt(0)
	v_add_f32_e32 v56, v56, v57
	ds_bpermute_b32 v57, v151, v56
	s_and_saveexec_b64 s[6:7], vcc
	s_cbranch_execz .LBB0_1348
	s_load_dwordx2 s[22:23], s[42:43], 0x120
	s_waitcnt lgkmcnt(0)
	v_add_f32_e32 v58, v56, v57
	v_lshlrev_b64 v[56:57], 8, v[140:141]
	v_lshl_add_u64 v[56:57], s[22:23], 0, v[56:57]
	v_lshl_add_u64 v[56:57], s[4:5], 2, v[56:57]
	v_lshl_add_u64 v[56:57], v[56:57], 0, v[128:129]
	global_store_dword v[56:57], v58, off
;     ...
;     for (int ai = 0; ai < 2; ++ai)
; #pragma unroll
;       for (int m = 0; m < 4; ++m) {
;         const int row = brow + ai * HALF + wr * 64 + m * 16 + fr;
;         float ssq = 0.f;
; #pragma unroll
;         for (int bj = 0; bj < 2; ++bj)
; #pragma unroll
;           for (int n = 0; n < 2; ++n) {
;             const int col = bcol + bj * HALF + wc * 32 + n * 16 + fq * 4;
;             f32x4 v = acc[ai][bj][m][n];
;             v += *(const f32x4*)(res + (long)row * D + col);
;             if (EPI == 7) *(f32x4*)(outf + (long)row * D + col) = v;
;             acc[ai][bj][m][n] = v;
;             ssq += v[0] * v[0] + v[1] * v[1] + v[2] * v[2] + v[3] * v[3];
;           }
;         ssq += bperm(ssq, lane ^ 16);
;         ssq += bperm(ssq, lane ^ 32);
;         if (fq == 0) p->sspart[(long)row * 64 + pn_ * 4 + wc] = ssq;
.LBB0_1348:
	s_or_b64 exec, exec, s[6:7]
	v_add_u32_e32 v144, 0x90, v142
	v_ashrrev_i32_e32 v145, 31, v144
	s_waitcnt lgkmcnt(0)
	v_lshlrev_b64 v[56:57], 14, v[144:145]
	v_lshl_add_u64 v[58:59], s[8:9], 0, v[56:57]
	v_lshl_add_u64 v[62:63], v[130:131], 2, v[58:59]
	global_load_dwordx4 v[58:61], v[62:63], off nt
	global_load_dwordx4 v[152:155], v[62:63], off offset:64 nt
	global_load_dwordx4 v[156:159], v[62:63], off offset:512 nt
	global_load_dwordx4 v[160:163], v[62:63], off offset:576 nt
	s_waitcnt vmcnt(3)
	v_pk_add_f32 v[62:63], v[34:35], v[60:61]
	v_pk_add_f32 v[140:141], v[32:33], v[58:59]
	s_waitcnt vmcnt(2)
	v_pk_add_f32 v[60:61], v[36:37], v[152:153]
	v_pk_add_f32 v[58:59], v[38:39], v[154:155]
	s_waitcnt vmcnt(1)
	v_pk_add_f32 v[38:39], v[44:45], v[156:157]
	s_waitcnt vmcnt(0)
	v_pk_add_f32 v[34:35], v[40:41], v[160:161]
	v_mul_f32_e32 v40, v141, v141
	v_mul_f32_e32 v41, v61, v61
	v_pk_add_f32 v[32:33], v[42:43], v[162:163]
	v_mul_f32_e32 v42, v39, v39
	v_fmac_f32_e32 v40, v140, v140
	v_fmac_f32_e32 v41, v60, v60
	v_pk_add_f32 v[36:37], v[46:47], v[158:159]
	v_mul_f32_e32 v43, v35, v35
	v_fmac_f32_e32 v42, v38, v38
	v_fmac_f32_e32 v40, v62, v62
	v_fmac_f32_e32 v41, v58, v58
	v_fmac_f32_e32 v43, v34, v34
	v_fmac_f32_e32 v42, v36, v36
	v_fmac_f32_e32 v40, v63, v63
	v_fmac_f32_e32 v41, v59, v59
	v_fmac_f32_e32 v43, v32, v32
	v_fmac_f32_e32 v42, v37, v37
	v_add_f32_e32 v40, v40, v41
	v_add_f32_e32 v40, v40, v42
	v_fmac_f32_e32 v43, v33, v33
	v_add_f32_e32 v40, v40, v43
	ds_bpermute_b32 v41, v150, v40
	s_waitcnt lgkmcnt(0)
	v_add_f32_e32 v40, v40, v41
	ds_bpermute_b32 v41, v151, v40
	s_and_saveexec_b64 s[6:7], vcc
	s_cbranch_execz .LBB0_1350
	s_load_dwordx2 s[22:23], s[42:43], 0x120
	s_waitcnt lgkmcnt(0)
	v_add_f32_e32 v42, v40, v41
	v_lshlrev_b64 v[40:41], 8, v[144:145]
	v_lshl_add_u64 v[40:41], s[22:23], 0, v[40:41]
	v_lshl_add_u64 v[40:41], s[4:5], 2, v[40:41]
	v_lshl_add_u64 v[40:41], v[40:41], 0, v[128:129]
	global_store_dword v[40:41], v42, off
.LBB0_1350:
	s_or_b64 exec, exec, s[6:7]
	v_add_u32_e32 v144, 0xa0, v142
	v_ashrrev_i32_e32 v145, 31, v144
	s_waitcnt lgkmcnt(0)
	v_lshlrev_b64 v[40:41], 14, v[144:145]
	v_lshl_add_u64 v[40:41], s[8:9], 0, v[40:41]
	v_lshl_add_u64 v[44:45], v[130:131], 2, v[40:41]
	global_load_dwordx4 v[40:43], v[44:45], off nt
	global_load_dwordx4 v[152:155], v[44:45], off offset:64 nt
	global_load_dwordx4 v[156:159], v[44:45], off offset:512 nt
	global_load_dwordx4 v[160:163], v[44:45], off offset:576 nt
	s_waitcnt vmcnt(3)
	v_pk_add_f32 v[44:45], v[18:19], v[42:43]
	v_pk_add_f32 v[46:47], v[16:17], v[40:41]
	s_waitcnt vmcnt(2)
	v_pk_add_f32 v[42:43], v[20:21], v[152:153]
	v_pk_add_f32 v[40:41], v[22:23], v[154:155]
	s_waitcnt vmcnt(1)
	v_pk_add_f32 v[22:23], v[28:29], v[156:157]
	s_waitcnt vmcnt(0)
	v_pk_add_f32 v[18:19], v[24:25], v[160:161]
	v_mul_f32_e32 v24, v47, v47
	v_mul_f32_e32 v25, v43, v43
	v_pk_add_f32 v[16:17], v[26:27], v[162:163]
	v_mul_f32_e32 v26, v23, v23
	v_fmac_f32_e32 v24, v46, v46
	v_fmac_f32_e32 v25, v42, v42
	v_pk_add_f32 v[20:21], v[30:31], v[158:159]
	v_mul_f32_e32 v27, v19, v19
	v_fmac_f32_e32 v26, v22, v22
	v_fmac_f32_e32 v24, v44, v44
	v_fmac_f32_e32 v25, v40, v40
	v_fmac_f32_e32 v27, v18, v18
	v_fmac_f32_e32 v26, v20, v20
	v_fmac_f32_e32 v24, v45, v45
	v_fmac_f32_e32 v25, v41, v41
	v_fmac_f32_e32 v27, v16, v16
	v_fmac_f32_e32 v26, v21, v21
	v_add_f32_e32 v24, v24, v25
	v_add_f32_e32 v24, v24, v26
	v_fmac_f32_e32 v27, v17, v17
	v_add_f32_e32 v24, v24, v27
	ds_bpermute_b32 v25, v150, v24
	s_waitcnt lgkmcnt(0)
	v_add_f32_e32 v24, v24, v25
	ds_bpermute_b32 v25, v151, v24
	s_and_saveexec_b64 s[6:7], vcc
	s_cbranch_execz .LBB0_1352
	s_load_dwordx2 s[22:23], s[42:43], 0x120
	s_waitcnt lgkmcnt(0)
	v_add_f32_e32 v26, v24, v25
	v_lshlrev_b64 v[24:25], 8, v[144:145]
	v_lshl_add_u64 v[24:25], s[22:23], 0, v[24:25]
	v_lshl_add_u64 v[24:25], s[4:5], 2, v[24:25]
	v_lshl_add_u64 v[24:25], v[24:25], 0, v[128:129]
	global_store_dword v[24:25], v26, off
.LBB0_1352:
	s_or_b64 exec, exec, s[6:7]
	v_add_u32_e32 v144, 0xb0, v142
	v_ashrrev_i32_e32 v145, 31, v144
	s_waitcnt lgkmcnt(0)
	v_lshlrev_b64 v[24:25], 14, v[144:145]
	v_lshl_add_u64 v[26:27], s[8:9], 0, v[24:25]
	v_lshl_add_u64 v[30:31], v[130:131], 2, v[26:27]
	global_load_dwordx4 v[26:29], v[30:31], off nt
	global_load_dwordx4 v[152:155], v[30:31], off offset:64 nt
	global_load_dwordx4 v[156:159], v[30:31], off offset:512 nt
	global_load_dwordx4 v[160:163], v[30:31], off offset:576 nt
	s_waitcnt vmcnt(3)
	v_pk_add_f32 v[30:31], v[2:3], v[28:29]
	v_pk_add_f32 v[142:143], v[0:1], v[26:27]
	s_waitcnt vmcnt(2)
	v_pk_add_f32 v[28:29], v[4:5], v[152:153]
	v_pk_add_f32 v[26:27], v[6:7], v[154:155]
	s_waitcnt vmcnt(1)
	v_pk_add_f32 v[6:7], v[12:13], v[156:157]
	s_waitcnt vmcnt(0)
	v_pk_add_f32 v[2:3], v[8:9], v[160:161]
	v_mul_f32_e32 v8, v143, v143
	v_mul_f32_e32 v9, v29, v29
	v_pk_add_f32 v[0:1], v[10:11], v[162:163]
	v_mul_f32_e32 v10, v7, v7
	v_fmac_f32_e32 v8, v142, v142
	v_fmac_f32_e32 v9, v28, v28
	v_pk_add_f32 v[4:5], v[14:15], v[158:159]
	v_mul_f32_e32 v11, v3, v3
	v_fmac_f32_e32 v10, v6, v6
	v_fmac_f32_e32 v8, v30, v30
	v_fmac_f32_e32 v9, v26, v26
	v_fmac_f32_e32 v11, v2, v2
	v_fmac_f32_e32 v10, v4, v4
	v_fmac_f32_e32 v8, v31, v31
	v_fmac_f32_e32 v9, v27, v27
	v_fmac_f32_e32 v11, v0, v0
	v_fmac_f32_e32 v10, v5, v5
	v_add_f32_e32 v8, v8, v9
	v_add_f32_e32 v8, v8, v10
	v_fmac_f32_e32 v11, v1, v1
	v_add_f32_e32 v8, v8, v11
	ds_bpermute_b32 v9, v150, v8
	s_waitcnt lgkmcnt(0)
	v_add_f32_e32 v8, v8, v9
	ds_bpermute_b32 v9, v151, v8
	s_and_saveexec_b64 s[6:7], vcc
	s_cbranch_execz .LBB0_1354
	s_load_dwordx2 s[22:23], s[42:43], 0x120
	s_waitcnt lgkmcnt(0)
	v_add_f32_e32 v10, v8, v9
	v_lshlrev_b64 v[8:9], 8, v[144:145]
	v_lshl_add_u64 v[8:9], s[22:23], 0, v[8:9]
	v_lshl_add_u64 v[8:9], s[4:5], 2, v[8:9]
	v_lshl_add_u64 v[8:9], v[8:9], 0, v[128:129]
	global_store_dword v[8:9], v10, off
